# P1: ff1 ReLU^2 epilogue trimmed - drop no-op canonicalising v_max x,x, use v_pk_mul_f32 for squares (192 fewer VALU per wave per unit), same packing
# speedup vs baseline: 1.0041x; 1.0041x over previous
.LBB0_237:
	s_lshl_b32 s6, s78, 8
	v_mbcnt_lo_u32_b32 v141, -1, 0
	v_mbcnt_hi_u32_b32 v141, -1, v141
	s_add_i32 s6, s6, s71
	v_and_or_b32 v140, v141, 15, s6
	s_lshl_b32 s6, s77, 8
	v_ashrrev_i32_e32 v141, 1, v141
	s_or_b32 s6, s6, s81
	v_and_b32_e32 v141, -8, v141
	v_add_u32_e32 v142, s6, v141
	v_ashrrev_i32_e32 v141, 31, v140
	v_lshlrev_b64 v[144:145], 13, v[140:141]
	v_ashrrev_i32_e32 v143, 31, v142
	v_lshl_add_u64 v[144:145], s[4:5], 0, v[144:145]
	s_movk_i32 s6, 0x1000
	v_lshl_add_u64 v[144:145], v[142:143], 1, v[144:145]
	v_cmp_gt_i32_e32 vcc, s6, v142
	s_and_saveexec_b64 s[6:7], vcc
	s_cbranch_execz .LBB0_239
	v_max_f32_e32 v122, 0, v122
	v_max_f32_e32 v123, 0, v123
	v_max_f32_e32 v124, 0, v124
	v_max_f32_e32 v125, 0, v125
	v_max_f32_e32 v126, 0, v126
	v_max_f32_e32 v127, 0, v127
	v_max_f32_e32 v128, 0, v128
	v_max_f32_e32 v129, 0, v129
	v_pk_mul_f32 v[122:123], v[122:123], v[122:123]
	v_pk_mul_f32 v[124:125], v[124:125], v[124:125]
	v_pk_mul_f32 v[126:127], v[126:127], v[126:127]
	v_pk_mul_f32 v[128:129], v[128:129], v[128:129]
	v_cvt_pk_bf16_f32 v125, v124, v125
	v_cvt_pk_bf16_f32 v124, v122, v123
	v_cvt_pk_bf16_f32 v122, v126, v127
	v_cvt_pk_bf16_f32 v123, v128, v129
	flat_store_dwordx4 v[144:145], v[122:125] sc1
.LBB0_239:
	s_or_b64 exec, exec, s[6:7]
	v_cmp_gt_i32_e64 s[38:39], s24, v142
	s_and_saveexec_b64 s[6:7], s[38:39]
	s_cbranch_execz .LBB0_241
	v_max_f32_e32 v114, 0, v114
	v_max_f32_e32 v115, 0, v115
	v_max_f32_e32 v116, 0, v116
	v_max_f32_e32 v117, 0, v117
	v_max_f32_e32 v118, 0, v118
	v_max_f32_e32 v119, 0, v119
	v_max_f32_e32 v120, 0, v120
	v_max_f32_e32 v121, 0, v121
	v_pk_mul_f32 v[114:115], v[114:115], v[114:115]
	v_pk_mul_f32 v[116:117], v[116:117], v[116:117]
	v_pk_mul_f32 v[118:119], v[118:119], v[118:119]
	v_pk_mul_f32 v[120:121], v[120:121], v[120:121]
	v_cvt_pk_bf16_f32 v117, v116, v117
	v_cvt_pk_bf16_f32 v116, v114, v115
	v_cvt_pk_bf16_f32 v114, v118, v119
	v_cvt_pk_bf16_f32 v115, v120, v121
	flat_store_dwordx4 v[144:145], v[114:117] offset:256 sc1
.LBB0_241:
	s_or_b64 exec, exec, s[6:7]
	s_nop 0
	v_or_b32_e32 v114, 16, v140
	v_ashrrev_i32_e32 v115, 31, v114
	v_lshlrev_b64 v[114:115], 13, v[114:115]
	v_lshl_add_u64 v[114:115], s[4:5], 0, v[114:115]
	v_lshl_add_u64 v[114:115], v[142:143], 1, v[114:115]
	s_and_saveexec_b64 s[6:7], vcc
	s_cbranch_execz .LBB0_243
	v_max_f32_e32 v106, 0, v106
	v_max_f32_e32 v107, 0, v107
	v_max_f32_e32 v108, 0, v108
	v_max_f32_e32 v109, 0, v109
	v_max_f32_e32 v110, 0, v110
	v_max_f32_e32 v111, 0, v111
	v_max_f32_e32 v112, 0, v112
	v_max_f32_e32 v113, 0, v113
	v_pk_mul_f32 v[106:107], v[106:107], v[106:107]
	v_pk_mul_f32 v[108:109], v[108:109], v[108:109]
	v_pk_mul_f32 v[110:111], v[110:111], v[110:111]
	v_pk_mul_f32 v[112:113], v[112:113], v[112:113]
	v_cvt_pk_bf16_f32 v109, v108, v109
	v_cvt_pk_bf16_f32 v108, v106, v107
	v_cvt_pk_bf16_f32 v106, v110, v111
	v_cvt_pk_bf16_f32 v107, v112, v113
	flat_store_dwordx4 v[114:115], v[106:109] sc1
.LBB0_243:
	s_or_b64 exec, exec, s[6:7]
	s_and_saveexec_b64 s[6:7], s[38:39]
	s_cbranch_execz .LBB0_245
	v_max_f32_e32 v98, 0, v98
	v_max_f32_e32 v99, 0, v99
	v_max_f32_e32 v100, 0, v100
	v_max_f32_e32 v101, 0, v101
	v_max_f32_e32 v102, 0, v102
	v_max_f32_e32 v103, 0, v103
	v_max_f32_e32 v104, 0, v104
	v_max_f32_e32 v105, 0, v105
	v_pk_mul_f32 v[98:99], v[98:99], v[98:99]
	v_pk_mul_f32 v[100:101], v[100:101], v[100:101]
	v_pk_mul_f32 v[102:103], v[102:103], v[102:103]
	v_pk_mul_f32 v[104:105], v[104:105], v[104:105]
	v_cvt_pk_bf16_f32 v101, v100, v101
	v_cvt_pk_bf16_f32 v100, v98, v99
	v_cvt_pk_bf16_f32 v98, v102, v103
	v_cvt_pk_bf16_f32 v99, v104, v105
	flat_store_dwordx4 v[114:115], v[98:101] offset:256 sc1
.LBB0_245:
	s_or_b64 exec, exec, s[6:7]
	s_nop 0
	v_or_b32_e32 v98, 32, v140
	v_ashrrev_i32_e32 v99, 31, v98
	v_lshlrev_b64 v[98:99], 13, v[98:99]
	v_lshl_add_u64 v[98:99], s[4:5], 0, v[98:99]
	v_lshl_add_u64 v[98:99], v[142:143], 1, v[98:99]
	s_and_saveexec_b64 s[6:7], vcc
	s_cbranch_execz .LBB0_247
	v_max_f32_e32 v90, 0, v90
	v_max_f32_e32 v91, 0, v91
	v_max_f32_e32 v92, 0, v92
	v_max_f32_e32 v93, 0, v93
	v_max_f32_e32 v94, 0, v94
	v_max_f32_e32 v95, 0, v95
	v_max_f32_e32 v96, 0, v96
	v_max_f32_e32 v97, 0, v97
	v_pk_mul_f32 v[90:91], v[90:91], v[90:91]
	v_pk_mul_f32 v[92:93], v[92:93], v[92:93]
	v_pk_mul_f32 v[94:95], v[94:95], v[94:95]
	v_pk_mul_f32 v[96:97], v[96:97], v[96:97]
	v_cvt_pk_bf16_f32 v93, v92, v93
	v_cvt_pk_bf16_f32 v92, v90, v91
	v_cvt_pk_bf16_f32 v90, v94, v95
	v_cvt_pk_bf16_f32 v91, v96, v97
	flat_store_dwordx4 v[98:99], v[90:93] sc1
.LBB0_247:
	s_or_b64 exec, exec, s[6:7]
	s_and_saveexec_b64 s[6:7], s[38:39]
	s_cbranch_execz .LBB0_249
	v_max_f32_e32 v82, 0, v82
	v_max_f32_e32 v83, 0, v83
	v_max_f32_e32 v84, 0, v84
	v_max_f32_e32 v85, 0, v85
	v_max_f32_e32 v86, 0, v86
	v_max_f32_e32 v87, 0, v87
	v_max_f32_e32 v88, 0, v88
	v_max_f32_e32 v89, 0, v89
	v_pk_mul_f32 v[82:83], v[82:83], v[82:83]
	v_pk_mul_f32 v[84:85], v[84:85], v[84:85]
	v_pk_mul_f32 v[86:87], v[86:87], v[86:87]
	v_pk_mul_f32 v[88:89], v[88:89], v[88:89]
	v_cvt_pk_bf16_f32 v85, v84, v85
	v_cvt_pk_bf16_f32 v84, v82, v83
	v_cvt_pk_bf16_f32 v82, v86, v87
	v_cvt_pk_bf16_f32 v83, v88, v89
	flat_store_dwordx4 v[98:99], v[82:85] offset:256 sc1
.LBB0_249:
	s_or_b64 exec, exec, s[6:7]
	s_nop 0
	v_or_b32_e32 v82, 48, v140
	v_ashrrev_i32_e32 v83, 31, v82
	v_lshlrev_b64 v[82:83], 13, v[82:83]
	v_lshl_add_u64 v[82:83], s[4:5], 0, v[82:83]
	v_lshl_add_u64 v[82:83], v[142:143], 1, v[82:83]
	s_and_saveexec_b64 s[6:7], vcc
	s_cbranch_execz .LBB0_251
	v_max_f32_e32 v72, 0, v72
	v_max_f32_e32 v73, 0, v73
	v_max_f32_e32 v74, 0, v74
	v_max_f32_e32 v75, 0, v75
	v_max_f32_e32 v76, 0, v76
	v_max_f32_e32 v77, 0, v77
	v_max_f32_e32 v78, 0, v78
	v_max_f32_e32 v79, 0, v79
	v_pk_mul_f32 v[72:73], v[72:73], v[72:73]
	v_pk_mul_f32 v[74:75], v[74:75], v[74:75]
	v_pk_mul_f32 v[76:77], v[76:77], v[76:77]
	v_pk_mul_f32 v[78:79], v[78:79], v[78:79]
	v_cvt_pk_bf16_f32 v75, v74, v75
	v_cvt_pk_bf16_f32 v74, v72, v73
	v_cvt_pk_bf16_f32 v72, v76, v77
	v_cvt_pk_bf16_f32 v73, v78, v79
	flat_store_dwordx4 v[82:83], v[72:75] sc1
.LBB0_251:
	s_or_b64 exec, exec, s[6:7]
	s_and_saveexec_b64 s[6:7], s[38:39]
	s_cbranch_execz .LBB0_253
	v_max_f32_e32 v64, 0, v64
	v_max_f32_e32 v65, 0, v65
	v_max_f32_e32 v66, 0, v66
	v_max_f32_e32 v67, 0, v67
	v_max_f32_e32 v68, 0, v68
	v_max_f32_e32 v69, 0, v69
	v_max_f32_e32 v70, 0, v70
	v_max_f32_e32 v71, 0, v71
	v_pk_mul_f32 v[64:65], v[64:65], v[64:65]
	v_pk_mul_f32 v[66:67], v[66:67], v[66:67]
	v_pk_mul_f32 v[68:69], v[68:69], v[68:69]
	v_pk_mul_f32 v[70:71], v[70:71], v[70:71]
	v_cvt_pk_bf16_f32 v67, v66, v67
	v_cvt_pk_bf16_f32 v66, v64, v65
	v_cvt_pk_bf16_f32 v64, v68, v69
	v_cvt_pk_bf16_f32 v65, v70, v71
	flat_store_dwordx4 v[82:83], v[64:67] offset:256 sc1
.LBB0_253:
	s_or_b64 exec, exec, s[6:7]
	s_nop 0
	v_lshlrev_b64 v[64:65], 13, v[140:141]
	v_lshl_add_u64 v[64:65], s[4:5], 0, v[64:65]
	v_lshl_add_u64 v[64:65], v[142:143], 1, v[64:65]
	s_mov_b64 s[6:7], 0x100000
	v_lshl_add_u64 v[64:65], v[64:65], 0, s[6:7]
	s_and_saveexec_b64 s[6:7], vcc
	s_cbranch_execz .LBB0_255
	v_max_f32_e32 v56, 0, v56
	v_max_f32_e32 v57, 0, v57
	v_max_f32_e32 v58, 0, v58
	v_max_f32_e32 v59, 0, v59
	v_max_f32_e32 v60, 0, v60
	v_max_f32_e32 v61, 0, v61
	v_max_f32_e32 v62, 0, v62
	v_max_f32_e32 v63, 0, v63
	v_pk_mul_f32 v[56:57], v[56:57], v[56:57]
	v_pk_mul_f32 v[58:59], v[58:59], v[58:59]
	v_pk_mul_f32 v[60:61], v[60:61], v[60:61]
	v_pk_mul_f32 v[62:63], v[62:63], v[62:63]
	v_cvt_pk_bf16_f32 v59, v58, v59
	v_cvt_pk_bf16_f32 v58, v56, v57
	v_cvt_pk_bf16_f32 v56, v60, v61
	v_cvt_pk_bf16_f32 v57, v62, v63
	flat_store_dwordx4 v[64:65], v[56:59] sc1
.LBB0_255:
	s_or_b64 exec, exec, s[6:7]
	s_and_saveexec_b64 s[6:7], s[38:39]
	s_cbranch_execz .LBB0_257
	v_max_f32_e32 v48, 0, v48
	v_max_f32_e32 v49, 0, v49
	v_max_f32_e32 v50, 0, v50
	v_max_f32_e32 v51, 0, v51
	v_max_f32_e32 v52, 0, v52
	v_max_f32_e32 v53, 0, v53
	v_max_f32_e32 v54, 0, v54
	v_max_f32_e32 v55, 0, v55
	v_pk_mul_f32 v[48:49], v[48:49], v[48:49]
	v_pk_mul_f32 v[50:51], v[50:51], v[50:51]
	v_pk_mul_f32 v[52:53], v[52:53], v[52:53]
	v_pk_mul_f32 v[54:55], v[54:55], v[54:55]
	v_cvt_pk_bf16_f32 v51, v50, v51
	v_cvt_pk_bf16_f32 v50, v48, v49
	v_cvt_pk_bf16_f32 v48, v52, v53
	v_cvt_pk_bf16_f32 v49, v54, v55
	flat_store_dwordx4 v[64:65], v[48:51] offset:256 sc1
.LBB0_257:
	s_or_b64 exec, exec, s[6:7]
	s_nop 0
	v_lshlrev_b64 v[48:49], 13, v[140:141]
	v_lshl_add_u64 v[48:49], s[4:5], 0, v[48:49]
	v_lshl_add_u64 v[48:49], v[142:143], 1, v[48:49]
	s_mov_b64 s[6:7], 0x120000
	v_lshl_add_u64 v[48:49], v[48:49], 0, s[6:7]
	s_and_saveexec_b64 s[6:7], vcc
	s_cbranch_execz .LBB0_259
	v_max_f32_e32 v40, 0, v40
	v_max_f32_e32 v41, 0, v41
	v_max_f32_e32 v42, 0, v42
	v_max_f32_e32 v43, 0, v43
	v_max_f32_e32 v44, 0, v44
	v_max_f32_e32 v45, 0, v45
	v_max_f32_e32 v46, 0, v46
	v_max_f32_e32 v47, 0, v47
	v_pk_mul_f32 v[40:41], v[40:41], v[40:41]
	v_pk_mul_f32 v[42:43], v[42:43], v[42:43]
	v_pk_mul_f32 v[44:45], v[44:45], v[44:45]
	v_pk_mul_f32 v[46:47], v[46:47], v[46:47]
	v_cvt_pk_bf16_f32 v43, v42, v43
	v_cvt_pk_bf16_f32 v42, v40, v41
	v_cvt_pk_bf16_f32 v40, v44, v45
	v_cvt_pk_bf16_f32 v41, v46, v47
	flat_store_dwordx4 v[48:49], v[40:43] sc1
.LBB0_259:
	s_or_b64 exec, exec, s[6:7]
	s_and_saveexec_b64 s[6:7], s[38:39]
	s_cbranch_execz .LBB0_261
	v_max_f32_e32 v32, 0, v32
	v_max_f32_e32 v33, 0, v33
	v_max_f32_e32 v34, 0, v34
	v_max_f32_e32 v35, 0, v35
	v_max_f32_e32 v36, 0, v36
	v_max_f32_e32 v37, 0, v37
	v_max_f32_e32 v38, 0, v38
	v_max_f32_e32 v39, 0, v39
	v_pk_mul_f32 v[32:33], v[32:33], v[32:33]
	v_pk_mul_f32 v[34:35], v[34:35], v[34:35]
	v_pk_mul_f32 v[36:37], v[36:37], v[36:37]
	v_pk_mul_f32 v[38:39], v[38:39], v[38:39]
	v_cvt_pk_bf16_f32 v35, v34, v35
	v_cvt_pk_bf16_f32 v34, v32, v33
	v_cvt_pk_bf16_f32 v32, v36, v37
	v_cvt_pk_bf16_f32 v33, v38, v39
	flat_store_dwordx4 v[48:49], v[32:35] offset:256 sc1
.LBB0_261:
	s_or_b64 exec, exec, s[6:7]
	s_nop 0
	v_lshlrev_b64 v[32:33], 13, v[140:141]
	v_lshl_add_u64 v[32:33], s[4:5], 0, v[32:33]
	v_lshl_add_u64 v[32:33], v[142:143], 1, v[32:33]
	s_mov_b64 s[6:7], 0x140000
	v_lshl_add_u64 v[32:33], v[32:33], 0, s[6:7]
	s_and_saveexec_b64 s[6:7], vcc
	s_cbranch_execz .LBB0_263
	v_max_f32_e32 v24, 0, v24
	v_max_f32_e32 v25, 0, v25
	v_max_f32_e32 v26, 0, v26
	v_max_f32_e32 v27, 0, v27
	v_max_f32_e32 v28, 0, v28
	v_max_f32_e32 v29, 0, v29
	v_max_f32_e32 v30, 0, v30
	v_max_f32_e32 v31, 0, v31
	v_pk_mul_f32 v[24:25], v[24:25], v[24:25]
	v_pk_mul_f32 v[26:27], v[26:27], v[26:27]
	v_pk_mul_f32 v[28:29], v[28:29], v[28:29]
	v_pk_mul_f32 v[30:31], v[30:31], v[30:31]
	v_cvt_pk_bf16_f32 v27, v26, v27
	v_cvt_pk_bf16_f32 v26, v24, v25
	v_cvt_pk_bf16_f32 v24, v28, v29
	v_cvt_pk_bf16_f32 v25, v30, v31
	flat_store_dwordx4 v[32:33], v[24:27] sc1
.LBB0_263:
	s_or_b64 exec, exec, s[6:7]
	s_and_saveexec_b64 s[6:7], s[38:39]
	s_cbranch_execz .LBB0_265
	v_max_f32_e32 v16, 0, v16
	v_max_f32_e32 v17, 0, v17
	v_max_f32_e32 v18, 0, v18
	v_max_f32_e32 v19, 0, v19
	v_max_f32_e32 v20, 0, v20
	v_max_f32_e32 v21, 0, v21
	v_max_f32_e32 v22, 0, v22
	v_max_f32_e32 v23, 0, v23
	v_pk_mul_f32 v[16:17], v[16:17], v[16:17]
	v_pk_mul_f32 v[18:19], v[18:19], v[18:19]
	v_pk_mul_f32 v[20:21], v[20:21], v[20:21]
	v_pk_mul_f32 v[22:23], v[22:23], v[22:23]
	v_cvt_pk_bf16_f32 v19, v18, v19
	v_cvt_pk_bf16_f32 v18, v16, v17
	v_cvt_pk_bf16_f32 v16, v20, v21
	v_cvt_pk_bf16_f32 v17, v22, v23
	flat_store_dwordx4 v[32:33], v[16:19] offset:256 sc1

.LBB0_268:
	v_max_f32_e32 v8, 0, v8
	v_max_f32_e32 v9, 0, v9
	v_max_f32_e32 v10, 0, v10
	v_max_f32_e32 v11, 0, v11
	v_max_f32_e32 v12, 0, v12
	v_max_f32_e32 v13, 0, v13
	v_max_f32_e32 v14, 0, v14
	v_max_f32_e32 v15, 0, v15
	v_pk_mul_f32 v[8:9], v[8:9], v[8:9]
	v_pk_mul_f32 v[10:11], v[10:11], v[10:11]
	v_pk_mul_f32 v[12:13], v[12:13], v[12:13]
	v_pk_mul_f32 v[14:15], v[14:15], v[14:15]
	v_cvt_pk_bf16_f32 v11, v10, v11
	v_cvt_pk_bf16_f32 v10, v8, v9
	v_cvt_pk_bf16_f32 v8, v12, v13
	v_cvt_pk_bf16_f32 v9, v14, v15
	flat_store_dwordx4 v[16:17], v[8:11] sc1
	s_or_b64 exec, exec, s[6:7]
	s_and_saveexec_b64 s[6:7], s[38:39]
	s_cbranch_execz .LBB0_267
.LBB0_269:
	v_max_f32_e32 v0, 0, v0
	v_max_f32_e32 v1, 0, v1
	v_max_f32_e32 v2, 0, v2
	v_max_f32_e32 v3, 0, v3
	v_max_f32_e32 v4, 0, v4
	v_max_f32_e32 v5, 0, v5
	v_max_f32_e32 v6, 0, v6
	v_max_f32_e32 v7, 0, v7
	v_pk_mul_f32 v[0:1], v[0:1], v[0:1]
	v_pk_mul_f32 v[2:3], v[2:3], v[2:3]
	v_pk_mul_f32 v[4:5], v[4:5], v[4:5]
	v_pk_mul_f32 v[6:7], v[6:7], v[6:7]
	v_cvt_pk_bf16_f32 v3, v2, v3
	v_cvt_pk_bf16_f32 v2, v0, v1
	v_cvt_pk_bf16_f32 v0, v4, v5
	v_cvt_pk_bf16_f32 v1, v6, v7
	flat_store_dwordx4 v[16:17], v[0:3] offset:256 sc1
	s_or_b64 exec, exec, s[6:7]
	s_andn2_b64 vcc, exec, s[36:37]
	s_mov_b64 s[6:7], -1
	s_cbranch_vccnz .LBB0_230
